# v28 plus hazard padding fixes in attention A tail step (hazard-clean)
# baseline (speedup 1.0000x reference)
.LBB0_793:
	s_cmp_gt_i32 s42, s43
	s_cbranch_scc1 .LBB0_797
	v_sub_u32_e32 v66, v181, v190
	v_lshl_add_u32 v71, s42, 6, v66
	v_add_u32_e32 v66, 0xffffff7f, v71
	v_cmp_lt_u32_e32 vcc, s29, v66
	s_nop 1
	v_cndmask_b32_e32 v66, v176, v34, vcc
	v_add_u32_e32 v34, 0xffffff9f, v71
	v_cmp_lt_u32_e32 vcc, s29, v34
	v_add_u32_e32 v34, 0xffffff80, v71
	s_nop 0
	v_cndmask_b32_e32 v50, v176, v50, vcc
	v_cmp_lt_u32_e32 vcc, s29, v34
	v_add_u32_e32 v34, 0xffffffa0, v71
	s_nop 0
	v_cndmask_b32_e32 v67, v176, v35, vcc
	v_cmp_lt_u32_e32 vcc, s29, v34
	v_add_u32_e32 v34, 0xffffff81, v71
	v_add_u32_e32 v35, 0xffffff9a, v71
	v_cndmask_b32_e32 v51, v176, v51, vcc
	v_cmp_lt_u32_e32 vcc, s29, v34
	v_add_u32_e32 v34, 0xffffffa1, v71
	s_nop 0
	v_cndmask_b32_e32 v68, v176, v36, vcc
	v_cmp_lt_u32_e32 vcc, s29, v34
	v_add_u32_e32 v34, 0xffffff82, v71
	s_nop 0
	v_cndmask_b32_e32 v52, v176, v52, vcc
	v_cmp_lt_u32_e32 vcc, s29, v34
	v_add_u32_e32 v34, 0xffffffa2, v71
	s_nop 0
	v_cndmask_b32_e32 v69, v176, v37, vcc
	v_cmp_lt_u32_e32 vcc, s29, v34
	v_add_u32_e32 v34, 0xffffff87, v71
	s_nop 0
	v_cndmask_b32_e32 v53, v176, v53, vcc
	v_cmp_lt_u32_e32 vcc, s29, v34
	v_add_u32_e32 v34, 0xffffffa7, v71
	s_nop 0
	v_cndmask_b32_e32 v70, v176, v38, vcc
	v_cmp_lt_u32_e32 vcc, s29, v34
	v_add_u32_e32 v34, 0xffffff88, v71
	s_nop 0
	v_cndmask_b32_e32 v38, v176, v54, vcc
	v_cmp_lt_u32_e32 vcc, s29, v34
	v_add_u32_e32 v34, 0xffffffa8, v71
	s_nop 0
	v_cndmask_b32_e32 v54, v176, v39, vcc
	v_cmp_lt_u32_e32 vcc, s29, v34
	v_add_u32_e32 v34, 0xffffff89, v71
	s_nop 0
	v_cndmask_b32_e32 v39, v176, v55, vcc
	v_cmp_lt_u32_e32 vcc, s29, v34
	v_add_u32_e32 v34, 0xffffffa9, v71
	s_nop 0
	v_cndmask_b32_e32 v55, v176, v40, vcc
	v_cmp_lt_u32_e32 vcc, s29, v34
	v_add_u32_e32 v34, 0xffffff8a, v71
	s_nop 0
	v_cndmask_b32_e32 v40, v176, v56, vcc
	v_cmp_lt_u32_e32 vcc, s29, v34
	v_add_u32_e32 v34, 0xffffffaa, v71
	s_nop 0
	v_cndmask_b32_e32 v56, v176, v41, vcc
	v_cmp_lt_u32_e32 vcc, s29, v34
	v_add_u32_e32 v34, 0xffffff8f, v71
	s_nop 0
	v_cndmask_b32_e32 v41, v176, v57, vcc
	v_cmp_lt_u32_e32 vcc, s29, v34
	v_add_u32_e32 v34, 0xffffffaf, v71
	s_nop 0
	v_cndmask_b32_e32 v57, v176, v42, vcc
	v_cmp_lt_u32_e32 vcc, s29, v34
	v_add_u32_e32 v34, 0xffffff90, v71
	s_nop 0
	v_cndmask_b32_e32 v42, v176, v58, vcc
	v_cmp_lt_u32_e32 vcc, s29, v34
	v_add_u32_e32 v34, 0xffffffb0, v71
	s_nop 0
	v_cndmask_b32_e32 v58, v176, v43, vcc
	v_cmp_lt_u32_e32 vcc, s29, v34
	v_add_u32_e32 v34, 0xffffff91, v71
	s_nop 0
	v_cndmask_b32_e32 v43, v176, v59, vcc
	v_cmp_lt_u32_e32 vcc, s29, v34
	v_add_u32_e32 v34, 0xffffffb1, v71
	s_nop 0
	v_cndmask_b32_e32 v59, v176, v44, vcc
	v_cmp_lt_u32_e32 vcc, s29, v34
	v_add_u32_e32 v34, 0xffffff92, v71
	s_nop 0
	v_cndmask_b32_e32 v44, v176, v60, vcc
	v_cmp_lt_u32_e32 vcc, s29, v34
	v_add_u32_e32 v34, 0xffffffb2, v71
	s_nop 0
	v_cndmask_b32_e32 v60, v176, v45, vcc
	v_cmp_lt_u32_e32 vcc, s29, v34
	v_add_u32_e32 v34, 0xffffff97, v71
	s_nop 0
	v_cndmask_b32_e32 v45, v176, v61, vcc
	v_cmp_lt_u32_e32 vcc, s29, v34
	v_add_u32_e32 v34, 0xffffffb7, v71
	s_nop 0
	v_cndmask_b32_e32 v61, v176, v46, vcc
	v_cmp_lt_u32_e32 vcc, s29, v34
	v_add_u32_e32 v34, 0xffffff98, v71
	s_nop 0
	v_cndmask_b32_e32 v46, v176, v62, vcc
	v_cmp_lt_u32_e32 vcc, s29, v34
	v_add_u32_e32 v34, 0xffffffb8, v71
	s_nop 0
	v_cndmask_b32_e32 v62, v176, v47, vcc
	v_cmp_lt_u32_e32 vcc, s29, v34
	v_add_u32_e32 v34, 0xffffff99, v71
	s_nop 0
	v_cndmask_b32_e32 v47, v176, v63, vcc
	v_cmp_lt_u32_e32 vcc, s29, v34
	v_add_u32_e32 v34, 0xffffffb9, v71
	s_nop 0
	v_cndmask_b32_e32 v37, v176, v48, vcc
	v_cmp_lt_u32_e32 vcc, s29, v34
	s_nop 1
	v_cndmask_b32_e32 v34, v176, v64, vcc
	v_cmp_lt_u32_e32 vcc, s29, v35
	v_add_u32_e32 v35, 0xffffffba, v71
	s_nop 0
	v_cndmask_b32_e32 v36, v176, v49, vcc
	v_cmp_lt_u32_e32 vcc, s29, v35
	s_nop 1
	v_cndmask_b32_e32 v35, v176, v65, vcc
.LBB0_796:
	v_exp_f32_e32 v64, v66
	v_exp_f32_e32 v66, v67
	v_exp_f32_e32 v65, v50
	v_exp_f32_e32 v67, v51
	v_exp_f32_e32 v50, v68
	v_exp_f32_e32 v68, v69
	v_exp_f32_e32 v51, v52
	v_mov_b32_e32 v48, v53
	v_exp_f32_e32 v53, v38
	v_exp_f32_e32 v69, v48
	v_exp_f32_e32 v71, v39
	v_exp_f32_e32 v52, v70
	v_mov_b32_e32 v48, v54
	v_exp_f32_e32 v54, v55
	v_exp_f32_e32 v72, v56
	v_exp_f32_e32 v55, v40
	v_exp_f32_e32 v73, v41
	v_exp_f32_e32 v56, v57
	v_exp_f32_e32 v74, v58
	v_exp_f32_e32 v57, v42
	v_exp_f32_e32 v75, v43
	v_exp_f32_e32 v58, v59
	v_exp_f32_e32 v76, v60
	v_exp_f32_e32 v59, v44
	v_exp_f32_e32 v77, v45
	v_exp_f32_e32 v60, v61
	s_bitcmp1_b32 s42, 0
	v_exp_f32_e32 v62, v62
	s_cselect_b32 s4, 0x3000, 0
	v_exp_f32_e32 v61, v46
	v_add_u32_e32 v82, s4, v183
	v_exp_f32_e32 v70, v48
	v_exp_f32_e32 v63, v47
	ds_read_b64_tr_b16 v[38:39], v82 offset:18432
	ds_read_b64_tr_b16 v[40:41], v82 offset:19968
	ds_read_b64_tr_b16 v[48:49], v82 offset:20032
	ds_read_b64_tr_b16 v[46:47], v82 offset:18496
	v_cvt_pk_bf16_f32 v42, v64, v66
	v_cvt_pk_bf16_f32 v43, v50, v68
	v_cvt_pk_bf16_f32 v44, v52, v70
	v_cvt_pk_bf16_f32 v45, v54, v72
	s_waitcnt lgkmcnt(2)
	s_nop 0
	v_mfma_f32_32x32x16_bf16 v[2:17], v[38:41], v[42:45], v[2:17]
	v_exp_f32_e32 v78, v37
	v_exp_f32_e32 v80, v36
	v_exp_f32_e32 v79, v34
	v_mov_b32_e32 v38, v35
	ds_read_b64_tr_b16 v[34:35], v82 offset:21504
	ds_read_b64_tr_b16 v[36:37], v82 offset:23040
	v_exp_f32_e32 v81, v38
	s_waitcnt lgkmcnt(2)
	v_mfma_f32_32x32x16_bf16 v[18:33], v[46:49], v[42:45], v[18:33]
	ds_read_b64_tr_b16 v[44:45], v82 offset:23104
	ds_read_b64_tr_b16 v[42:43], v82 offset:21568
	v_cvt_pk_bf16_f32 v38, v56, v74
	v_cvt_pk_bf16_f32 v39, v58, v76
	v_cvt_pk_bf16_f32 v40, v60, v62
	v_cvt_pk_bf16_f32 v41, v78, v80
	s_waitcnt lgkmcnt(2)
	s_nop 0
	v_mfma_f32_32x32x16_bf16 v[2:17], v[34:37], v[38:41], v[2:17]
	v_add_f32_e64 v34, v64, 0
	v_add_f32_e64 v35, v65, 0
	v_add_f32_e64 v36, v66, 0
	v_add_f32_e64 v37, v67, 0
	v_add_f32_e64 v34, v50, v34
	v_add_f32_e64 v35, v51, v35
	v_pk_add_f32 v[46:47], v[68:69], v[36:37]
	v_pk_add_f32 v[48:49], v[52:53], v[34:35]
	ds_read_b64_tr_b16 v[34:35], v82 offset:24576
	ds_read_b64_tr_b16 v[36:37], v82 offset:26112
	v_pk_add_f32 v[46:47], v[70:71], v[46:47]
	s_waitcnt lgkmcnt(2)
	v_mfma_f32_32x32x16_bf16 v[18:33], v[42:45], v[38:41], v[18:33]
	ds_read_b64_tr_b16 v[44:45], v82 offset:26176
	ds_read_b64_tr_b16 v[42:43], v82 offset:24640
	v_cvt_pk_bf16_f32 v38, v65, v67
	v_cvt_pk_bf16_f32 v39, v51, v69
	v_cvt_pk_bf16_f32 v40, v53, v71
	v_cvt_pk_bf16_f32 v41, v55, v73
	s_waitcnt lgkmcnt(2)
	s_nop 0
	v_mfma_f32_32x32x16_bf16 v[2:17], v[34:37], v[38:41], v[2:17]
	v_add_f32_e64 v34, v54, v48
	v_add_f32_e64 v35, v55, v49
	v_add_f32_e64 v36, v72, v46
	v_add_f32_e64 v37, v73, v47
	v_add_f32_e64 v34, v56, v34
	v_add_f32_e64 v35, v57, v35
	v_pk_add_f32 v[46:47], v[74:75], v[36:37]
	v_pk_add_f32 v[48:49], v[58:59], v[34:35]
	ds_read_b64_tr_b16 v[34:35], v82 offset:27648
	ds_read_b64_tr_b16 v[36:37], v82 offset:29184
	v_pk_add_f32 v[46:47], v[76:77], v[46:47]
	s_waitcnt lgkmcnt(2)
	v_mfma_f32_32x32x16_bf16 v[18:33], v[42:45], v[38:41], v[18:33]
	ds_read_b64_tr_b16 v[44:45], v82 offset:29248
	ds_read_b64_tr_b16 v[42:43], v82 offset:27712
	v_cvt_pk_bf16_f32 v38, v57, v75
	v_cvt_pk_bf16_f32 v39, v59, v77
	v_cvt_pk_bf16_f32 v40, v61, v63
	v_cvt_pk_bf16_f32 v41, v79, v81
	s_waitcnt lgkmcnt(0)
	s_barrier
	v_mfma_f32_32x32x16_bf16 v[2:17], v[34:37], v[38:41], v[2:17]
	v_add_f32_e64 v34, v60, v48
	v_add_f32_e64 v35, v61, v49
	v_add_f32_e64 v36, v62, v46
	v_add_f32_e64 v37, v63, v47
	v_add_f32_e64 v34, v78, v34
	v_add_f32_e64 v35, v79, v35
	v_pk_add_f32 v[36:37], v[80:81], v[36:37]
	s_nop 0
	v_pk_add_f32 v[34:35], v[34:35], v[36:37]
	v_mfma_f32_32x32x16_bf16 v[18:33], v[42:45], v[38:41], v[18:33]
	v_add_f32_e32 v34, v34, v35
	v_add_f32_e32 v0, v0, v34
